# P0 w_in transpose items: next round's 8 global loads prefetched right after the LDS writes (v160-191), skipping the load issue in the next round
# baseline (speedup 1.0000x reference)
.LBB0_17:
	s_load_dwordx16 s[36:51], s[0:1], 0x0
	s_load_dwordx16 s[52:67], s[0:1], 0x40
	v_readlane_b32 s0, v254, 0
	v_mov_b32_e32 v0, v200
	s_cmpk_gt_i32 s0, 0x114c
	s_cbranch_scc1 .LBB0_110
	v_and_b32_e32 v2, 15, v0
	v_cvt_f32_ubyte0_e32 v2, v2
	v_mul_f32_e32 v3, 0xbf549a78, v2
	s_mov_b32 s0, 0xc2fc0000
	v_mov_b32_e32 v4, 0x42800000
	v_cmp_gt_f32_e32 vcc, s0, v3
	v_mov_b32_e32 v1, 2
	v_lshlrev_b32_sdwa v72, v1, v0 dst_sel:DWORD dst_unused:UNUSED_PAD src0_sel:DWORD src1_sel:BYTE_0
	v_cndmask_b32_e32 v3, 0, v4, vcc
	v_fmac_f32_e32 v3, 0xbf549a78, v2
	v_exp_f32_e32 v2, v3
	v_not_b32_e32 v1, 63
	v_cndmask_b32_e32 v1, 0, v1, vcc
	s_movk_i32 s94, 0x100
	v_ldexp_f32 v1, v2, v1
	v_bfe_u32 v2, v0, 4, 4
	v_cvt_f32_ubyte0_e32 v2, v2
	v_mul_f32_e32 v2, v1, v2
	v_mul_f32_e32 v3, 0.15915494, v2
	v_floor_f32_e32 v3, v3
	v_fma_f32 v2, v2, 0.15915494, -v3
	v_cos_f32_e32 v84, v2
	v_sin_f32_e32 v85, v2
	v_or_b32_sdwa v2, v0, s94 dst_sel:DWORD dst_unused:UNUSED_PAD src0_sel:BYTE_0 src1_sel:DWORD
	v_lshrrev_b32_e32 v3, 4, v2
	v_cvt_f32_ubyte0_e32 v3, v3
	v_mul_f32_e32 v3, v1, v3
	v_mul_f32_e32 v4, 0.15915494, v3
	s_add_u32 s2, s22, 0x17cdb000
	v_floor_f32_e32 v4, v4
	s_addc_u32 s3, s23, 0
	v_fma_f32 v3, v3, 0.15915494, -v4
	s_movk_i32 s95, 0x200
	s_add_u32 s4, s22, 0x16cf3000
	v_cos_f32_e32 v86, v3
	v_sin_f32_e32 v87, v3
	v_or_b32_sdwa v3, v0, s95 dst_sel:DWORD dst_unused:UNUSED_PAD src0_sel:BYTE_0 src1_sel:DWORD
	s_addc_u32 s5, s23, 0
	v_lshrrev_b32_e32 v4, 4, v3
	s_add_u32 s0, s22, 0x71000
	v_cvt_f32_ubyte0_e32 v4, v4
	s_addc_u32 s1, s23, 0
	v_mul_f32_e32 v4, v1, v4
	s_add_u32 s24, s22, 0x17073000
	v_mul_f32_e32 v5, 0.15915494, v4
	s_addc_u32 s25, s23, 0
	v_floor_f32_e32 v5, v5
	s_add_u32 s26, s22, 0x17473000
	v_fma_f32 v4, v4, 0.15915494, -v5
	s_movk_i32 s96, 0x300
	s_addc_u32 s27, s23, 0
	v_cos_f32_e32 v88, v4
	v_sin_f32_e32 v89, v4
	v_or_b32_sdwa v4, v0, s96 dst_sel:DWORD dst_unused:UNUSED_PAD src0_sel:BYTE_0 src1_sel:DWORD
	s_add_u32 s28, s22, 0x16ef3000
	v_mov_b32_e32 v73, 3
	v_lshrrev_b32_e32 v5, 4, v4
	s_addc_u32 s29, s23, 0
	v_lshlrev_b32_sdwa v74, v73, v0 dst_sel:DWORD dst_unused:UNUSED_PAD src0_sel:DWORD src1_sel:BYTE_0
	v_bfe_u32 v79, v0, 4, 1
	v_cvt_f32_ubyte0_e32 v5, v5
	v_lshlrev_b32_e32 v0, 12, v0
	s_add_u32 s30, s22, 0x16f73000
	v_mov_b32_e32 v77, 0
	v_mul_f32_e32 v1, v1, v5
	v_and_b32_e32 v76, 0xf000, v0
	s_addc_u32 s31, s23, 0
	v_mul_f32_e32 v5, 0.15915494, v1
	s_waitcnt lgkmcnt(0)
	v_lshl_add_u64 v[92:93], s[58:59], 0, v[76:77]
	v_lshlrev_b32_e32 v76, 3, v2
	s_add_u32 s34, s22, 0x15cf3000
	v_floor_f32_e32 v5, v5
	v_lshl_add_u64 v[96:97], s[0:1], 0, v[76:77]
	v_lshlrev_b32_e32 v76, 3, v3
	s_addc_u32 s35, s23, 0
	v_mov_b32_e32 v75, v77
	v_fma_f32 v1, v1, 0.15915494, -v5
	v_lshl_add_u64 v[98:99], s[0:1], 0, v[76:77]
	v_lshlrev_b32_e32 v76, 3, v4
	s_add_u32 s58, s22, 0x130f3000
	v_readlane_b32 s92, v254, 0
	v_cos_f32_e32 v90, v1
	v_sin_f32_e32 v91, v1
	v_lshl_add_u64 v[94:95], s[0:1], 0, v[74:75]
	v_lshl_add_u64 v[100:101], s[0:1], 0, v[76:77]
	s_addc_u32 s59, s23, 0
	s_lshl_b32 s0, s92, 1
	s_add_i32 s97, s0, 0xffffe57e
	s_lshl_b32 s90, s33, 1
	s_add_u32 s44, s44, 0xffffe000
	v_or_b32_e32 v78, 0x400, v72
	v_or_b32_e32 v80, 0x800, v72
	v_or_b32_e32 v82, 0xc00, v72
	s_addc_u32 s45, s45, -1
	v_mov_b32_e32 v75, 0xffffe9c0
	v_mov_b32_e32 v81, 0xffffe980
	v_mov_b32_e32 v83, 0x100
	v_mov_b32_e32 v106, 0x400
	v_mov_b32_e32 v107, 0x3d800000
	v_mov_b32_e32 v108, 0x3d000000
	v_mov_b32_e32 v109, 0x3b800000
	v_mov_b32_e32 v110, 0x3a800000
	v_mov_b32_e32 v111, 0x17873000
	v_mov_b32_e32 v112, 0x178bb000
	v_mov_b32_e32 v113, 0x240
	v_mov_b32_e32 v114, 0x840
	v_mov_b32_e32 v115, 0x2c00000
	v_mov_b32_e32 v116, 0x1600000
	v_mov_b32_e32 v117, 10
	s_movk_i32 s91, 0x6000
	s_movk_i32 s84, 0x204
	s_movk_i32 s85, 0x1600
	s_mov_b32 s88, 0xc000
	s_mov_b32 s89, 0x12000
	s_mov_b32 s98, 0
	s_branch .LBB0_20

.LBB0_101:
	s_andn2_saveexec_b64 s[0:1], s[70:71]
	s_cbranch_execz .LBB0_103
	v_add_u32_e32 v0, 0xfffffe80, v4
	s_movk_i32 s70, 0x580
	v_add_u32_e32 v1, 0xfffff900, v4
	v_cmp_gt_u32_e32 vcc, s70, v0
	s_mov_b32 s70, 0xba2e8ba3
	v_mov_b32_e32 v37, v200
	v_cndmask_b32_e32 v1, v1, v0, vcc
	v_mul_hi_u32 v2, v1, s70
	s_movk_i32 s70, 0x57f
	v_lshrrev_b32_e32 v2, 5, v2
	v_cmp_lt_u32_e32 vcc, s70, v0
	v_mul_lo_u32 v3, v2, 44
	v_sub_u32_e32 v3, v1, v3
	v_cndmask_b32_e32 v76, 0, v115, vcc
	v_lshl_add_u64 v[0:1], s[54:55], 0, v[76:77]
	v_cndmask_b32_e32 v76, 0, v116, vcc
	v_mov_b32_e32 v38, v200
	v_lshl_add_u64 v[32:33], s[58:59], 0, v[76:77]
	v_lshlrev_b32_e32 v36, 6, v2
	v_lshlrev_b32_e32 v76, 7, v3
	v_lshl_add_u64 v[0:1], v[76:77], 2, v[0:1]
	v_lshlrev_b32_e32 v2, 4, v38
	v_and_b32_e32 v34, 0x1f0, v2
	v_mov_b32_e32 v35, v77
	v_or_b32_sdwa v39, v38, s94 dst_sel:DWORD dst_unused:UNUSED_PAD src0_sel:BYTE_0 src1_sel:DWORD
	v_or_b32_sdwa v41, v38, s95 dst_sel:DWORD dst_unused:UNUSED_PAD src0_sel:BYTE_0 src1_sel:DWORD
	v_or_b32_sdwa v43, v38, s96 dst_sel:DWORD dst_unused:UNUSED_PAD src0_sel:BYTE_0 src1_sel:DWORD
	v_lshl_add_u64 v[28:29], v[0:1], 0, v[34:35]
	v_bfe_u32 v35, v38, 5, 3
	v_lshrrev_b32_e32 v40, 5, v39
	v_lshrrev_b32_e32 v42, 5, v41
	v_lshrrev_b32_e32 v44, 5, v43
	v_or_b32_e32 v30, v35, v36
	v_or_b32_e32 v2, v40, v36
	v_or_b32_e32 v8, v42, v36
	v_or_b32_e32 v10, v44, v36
	v_mul_lo_u32 v0, v30, s85
	v_mov_b32_e32 v1, v77
	v_mul_lo_u32 v2, v2, s85
	v_mov_b32_e32 v3, v77
	v_mul_lo_u32 v8, v8, s85
	v_mov_b32_e32 v9, v77
	v_mul_lo_u32 v10, v10, s85
	v_mov_b32_e32 v11, v77
	v_or_b32_e32 v16, 32, v30
	v_lshl_add_u64 v[0:1], v[0:1], 2, v[28:29]
	v_lshl_add_u64 v[4:5], v[2:3], 2, v[28:29]
	v_lshl_add_u64 v[8:9], v[8:9], 2, v[28:29]
	v_lshl_add_u64 v[12:13], v[10:11], 2, v[28:29]
	v_mul_lo_u32 v16, v16, s85
	v_mov_b32_e32 v17, v77
	v_or_b32_e32 v20, 40, v30
	s_barrier
	s_cmp_lg_u32 s98, 0
	s_cbranch_scc1 .Lp0pf_have
	global_load_dwordx4 v[160:163], v[0:1], off
	global_load_dwordx4 v[164:167], v[4:5], off
	global_load_dwordx4 v[168:171], v[8:9], off
	global_load_dwordx4 v[172:175], v[12:13], off
	v_lshl_add_u64 v[16:17], v[16:17], 2, v[28:29]
	v_mul_lo_u32 v20, v20, s85
	v_mov_b32_e32 v21, v77
	global_load_dwordx4 v[176:179], v[16:17], off
	v_lshl_add_u64 v[20:21], v[20:21], 2, v[28:29]
	v_or_b32_e32 v24, 48, v30
	global_load_dwordx4 v[180:183], v[20:21], off
	v_mul_lo_u32 v24, v24, s85
	v_mov_b32_e32 v25, v77
	v_lshl_add_u64 v[24:25], v[24:25], 2, v[28:29]
	v_or_b32_e32 v30, 56, v30
	global_load_dwordx4 v[184:187], v[24:25], off
	v_mul_lo_u32 v30, v30, s85
	v_mov_b32_e32 v31, v77
	v_lshl_add_u64 v[28:29], v[30:31], 2, v[28:29]
	global_load_dwordx4 v[188:191], v[28:29], off
	s_waitcnt vmcnt(0)
.Lp0pf_have:
	s_mov_b32 s98, 0
	v_lshlrev_b32_e32 v37, 8, v37
	v_and_b32_e32 v37, 0xffff0000, v37
	v_add_u32_e32 v37, 16, v37
	v_add_u32_e32 v34, v37, v34
	v_mad_u32_u24 v35, v35, s84, v34
	v_mad_u32_u24 v40, v40, s84, v34
	v_mad_u32_u24 v42, v42, s84, v34
	v_mad_u32_u24 v34, v44, s84, v34
	v_add_u32_e32 v44, 0x4080, v35
	s_waitcnt vmcnt(11)
	ds_write2_b32 v35, v160, v161 offset1:1
	ds_write2_b32 v35, v162, v163 offset0:2 offset1:3
	s_waitcnt vmcnt(10)
	ds_write2_b32 v40, v164, v165 offset1:1
	ds_write2_b32 v40, v166, v167 offset0:2 offset1:3
	s_waitcnt vmcnt(9)
	ds_write2_b32 v42, v168, v169 offset1:1
	ds_write2_b32 v42, v170, v171 offset0:2 offset1:3
	s_waitcnt vmcnt(8)
	ds_write2_b32 v34, v172, v173 offset1:1
	ds_write2_b32 v34, v174, v175 offset0:2 offset1:3
	s_waitcnt vmcnt(7)
	ds_write2_b32 v44, v176, v177 offset1:1
	v_add_u32_e32 v0, 0x4088, v35
	v_lshlrev_b32_sdwa v10, v73, v38 dst_sel:DWORD dst_unused:UNUSED_PAD src0_sel:DWORD src1_sel:BYTE_0
	ds_write2_b32 v0, v178, v179 offset1:1
	v_add_u32_e32 v0, 0x50a0, v35
	s_waitcnt vmcnt(6)
	ds_write2_b32 v0, v180, v181 offset1:1
	v_add_u32_e32 v0, 0x50a8, v35
	ds_write2_b32 v0, v182, v183 offset1:1
	v_add_u32_e32 v0, 0x60c0, v35
	s_waitcnt vmcnt(5)
	ds_write2_b32 v0, v184, v185 offset1:1
	v_add_u32_e32 v0, 0x60c8, v35
	ds_write2_b32 v0, v186, v187 offset1:1
	v_add_u32_e32 v0, 0x70e0, v35
	s_waitcnt vmcnt(4)
	ds_write2_b32 v0, v188, v189 offset1:1
	v_add_u32_e32 v0, 0x70e8, v35
	ds_write2_b32 v0, v190, v191 offset1:1
	v_and_b32_e32 v0, 56, v10
	v_mad_u32_u24 v16, v0, s84, v37
	v_or_b32_e32 v0, v0, v36
	v_lshrrev_b32_e32 v0, 5, v0
	v_mad_u64_u32 v[4:5], s[70:71], v0, s85, v[76:77]
	v_bfe_u32 v5, v38, 3, 5
	v_lshl_add_u32 v8, v5, 2, v16
	s_waitcnt lgkmcnt(0)
	s_add_i32 s99, s92, s33
	s_cmpk_lt_i32 s99, 0x114d
	s_cbranch_scc0 .Lp0pf_none
	s_mov_b32 s100, s99
	s_bfe_u32 s101, s99, 0x10003
	s_cmp_eq_u32 s101, 0
	s_cbranch_scc1 .Lp0pf_rdone
	s_and_b32 s101, s99, 0xff
	s_lshr_b32 s100, s99, 8
	s_add_i32 s100, s100, 13
	s_cmpk_lt_u32 s101, 0x4d
	s_cselect_b32 s32, 18, 17
	s_cmp_lt_u32 s100, s32
	s_cbranch_scc1 .Lp0pf_nowrap
	s_sub_u32 s100, s100, s32

.Lp0pf_rdone:
	s_sub_u32 s99, s100, 0xc0
	s_cmpk_lt_u32 s99, 0x580
	s_cbranch_scc0 .Lp0pf_none
	s_lshl_b32 s99, s99, 1
	s_cmpk_lt_u32 s99, 0x580
	s_cselect_b32 s101, 0, 1
	s_mul_i32 s32, s101, 0x580
	s_sub_u32 s99, s99, s32
	s_mul_hi_u32 s100, s99, 0xba2e8ba3
	s_lshr_b32 s100, s100, 5
	s_mul_i32 s32, s100, 44
	s_sub_u32 s99, s99, s32
	s_mul_i32 s101, s101, 0x2c00000
	s_mul_i32 s100, s100, 0x160000
	s_add_u32 s101, s101, s100
	s_lshl_b32 s99, s99, 9
	s_add_u32 s101, s101, s99
	s_add_u32 s100, s54, s101
	s_addc_u32 s101, s55, 0
	s_movk_i32 s32, 0x5800
	v_and_b32_e32 v192, 31, v200
	v_bfe_u32 v193, v200, 5, 3
	v_lshlrev_b32_e32 v192, 4, v192
	v_mad_u32_u24 v192, v193, s32, v192
	v_lshrrev_b32_e32 v193, 8, v200
	v_lshl_add_u32 v192, v193, 9, v192
	v_add_u32_e32 v193, 0x2c000, v192
	v_add_u32_e32 v194, 0x58000, v192
	v_add_u32_e32 v195, 0x84000, v192
	v_add_u32_e32 v196, 0xb0000, v192
	v_add_u32_e32 v197, 0xdc000, v192
	v_add_u32_e32 v198, 0x108000, v192
	v_add_u32_e32 v199, 0x134000, v192
	global_load_dwordx4 v[160:163], v192, s[100:101]
	global_load_dwordx4 v[164:167], v193, s[100:101]
	global_load_dwordx4 v[168:171], v194, s[100:101]
	global_load_dwordx4 v[172:175], v195, s[100:101]
	global_load_dwordx4 v[176:179], v196, s[100:101]
	global_load_dwordx4 v[180:183], v197, s[100:101]
	global_load_dwordx4 v[184:187], v198, s[100:101]
	global_load_dwordx4 v[188:191], v199, s[100:101]
	s_mov_b32 s98, 1
.Lp0pf_none:
	s_barrier
	ds_read2_b32 v[0:1], v8 offset1:129
	v_add_u32_e32 v2, 0x400, v8
	v_add_u32_e32 v6, 0x800, v8
	v_add_u32_e32 v8, 0xc00, v8
	ds_read2_b32 v[2:3], v2 offset0:2 offset1:131
	ds_read2_b32 v[8:9], v8 offset0:6 offset1:135
	v_and_b32_e32 v10, 24, v10
	v_or_b32_e32 v5, v4, v5
	v_lshlrev_b32_e32 v17, 1, v10
	v_lshl_or_b32 v76, v5, 6, v17
	v_lshrrev_b32_e32 v5, 3, v39
	v_lshl_add_u32 v14, v5, 2, v16
	ds_read2_b32 v[6:7], v6 offset0:4 offset1:133
	s_waitcnt lgkmcnt(3)
	v_cvt_pk_bf16_f32 v0, v0, v1
	s_waitcnt lgkmcnt(2)
	v_cvt_pk_bf16_f32 v1, v2, v3
	s_waitcnt lgkmcnt(1)
	v_cvt_pk_bf16_f32 v3, v8, v9
	ds_read2_b32 v[8:9], v14 offset1:129
	v_add_u32_e32 v10, 0x400, v14
	v_add_u32_e32 v12, 0x800, v14
	v_add_u32_e32 v14, 0xc00, v14
	ds_read2_b32 v[14:15], v14 offset0:6 offset1:135
	ds_read2_b32 v[10:11], v10 offset0:2 offset1:131
	ds_read2_b32 v[12:13], v12 offset0:4 offset1:133
	v_or_b32_e32 v5, v4, v5
	s_waitcnt lgkmcnt(4)
	v_cvt_pk_bf16_f32 v2, v6, v7
	v_lshl_add_u64 v[6:7], v[32:33], 0, v[76:77]
	v_lshl_or_b32 v76, v5, 6, v17
	v_lshrrev_b32_e32 v5, 3, v41
	global_store_dwordx4 v[6:7], v[0:3], off
	v_lshl_add_u64 v[6:7], v[32:33], 0, v[76:77]
	s_waitcnt lgkmcnt(2)
	v_cvt_pk_bf16_f32 v3, v14, v15
	v_lshl_add_u32 v14, v5, 2, v16
	v_cvt_pk_bf16_f32 v0, v8, v9
	s_waitcnt lgkmcnt(1)
	v_cvt_pk_bf16_f32 v1, v10, v11
	s_waitcnt lgkmcnt(0)
	v_cvt_pk_bf16_f32 v2, v12, v13
	ds_read2_b32 v[8:9], v14 offset1:129
	v_add_u32_e32 v10, 0x400, v14
	v_add_u32_e32 v12, 0x800, v14
	v_add_u32_e32 v14, 0xc00, v14
	ds_read2_b32 v[10:11], v10 offset0:2 offset1:131
	ds_read2_b32 v[12:13], v12 offset0:4 offset1:133
	ds_read2_b32 v[14:15], v14 offset0:6 offset1:135
	v_or_b32_e32 v5, v4, v5
	v_lshl_or_b32 v76, v5, 6, v17
	v_lshrrev_b32_e32 v5, 3, v43
	global_store_dwordx4 v[6:7], v[0:3], off
	v_lshl_add_u64 v[6:7], v[32:33], 0, v[76:77]
	v_or_b32_e32 v4, v4, v5
	s_waitcnt lgkmcnt(3)
	v_cvt_pk_bf16_f32 v0, v8, v9
	s_waitcnt lgkmcnt(2)
	v_cvt_pk_bf16_f32 v1, v10, v11
	s_waitcnt lgkmcnt(1)
	v_cvt_pk_bf16_f32 v2, v12, v13
	s_waitcnt lgkmcnt(0)
	v_cvt_pk_bf16_f32 v3, v14, v15
	v_lshl_add_u32 v8, v5, 2, v16
	global_store_dwordx4 v[6:7], v[0:3], off
	ds_read2_b32 v[0:1], v8 offset1:129
	v_add_u32_e32 v6, 0x800, v8
	v_add_u32_e32 v2, 0x400, v8
	v_add_u32_e32 v8, 0xc00, v8
	ds_read2_b32 v[2:3], v2 offset0:2 offset1:131
	ds_read2_b32 v[6:7], v6 offset0:4 offset1:133
	ds_read2_b32 v[8:9], v8 offset0:6 offset1:135
	v_lshl_or_b32 v76, v4, 6, v17
	s_waitcnt lgkmcnt(3)
	v_cvt_pk_bf16_f32 v0, v0, v1
	s_waitcnt lgkmcnt(2)
	v_cvt_pk_bf16_f32 v1, v2, v3
	s_waitcnt lgkmcnt(1)
	v_cvt_pk_bf16_f32 v2, v6, v7
	s_waitcnt lgkmcnt(0)
	v_cvt_pk_bf16_f32 v3, v8, v9
	v_lshl_add_u64 v[4:5], v[32:33], 0, v[76:77]
	global_store_dwordx4 v[4:5], v[0:3], off
